# v39 + nt (streaming) hint on the attention Q-fragment loads (read once per unit) to keep the K/V images L2-resident
# baseline (speedup 1.0000x reference)
.LBB0_783:
	s_ashr_i32 s2, s4, 7
	s_sub_i32 s5, 1, s2
	s_and_b32 s2, s4, 0x78
	v_readlane_b32 s3, v250, 0
	s_add_i32 s2, s2, s3
	s_and_b32 s6, s4, 7
	v_lshl_or_b32 v158, s2, 5, v182
	s_mul_i32 s40, s6, 0x1100
	v_ashrrev_i32_e32 v159, 31, v158
	v_lshl_add_u64 v[0:1], s[40:41], 0, v[158:159]
	v_mad_u64_u32 v[2:3], s[2:3], v0, s21, v[186:187]
	s_mul_i32 s8, s6, 0x198000
	v_readlane_b32 s2, v251, 37
	v_readlane_b32 s3, v251, 38
	s_add_u32 s2, s2, s8
	s_addc_u32 s3, s3, 0
	s_mul_i32 s40, s5, 34
	s_mul_i32 s5, s5, 0xcc000
	s_mul_hi_u32 s9, s40, 0x6000
	s_add_u32 s2, s2, s5
	v_mad_i32_i24 v3, v1, s21, v3
	s_addc_u32 s3, s3, s9
	global_load_dwordx4 v[82:85], v[2:3], off nt
	global_load_dwordx4 v[86:89], v[2:3], off offset:32 nt
	global_load_dwordx4 v[90:93], v[2:3], off offset:64 nt
	global_load_dwordx4 v[112:115], v[2:3], off offset:96 nt
	global_load_dwordx4 v[116:119], v[2:3], off offset:128 nt
	global_load_dwordx4 v[120:123], v[2:3], off offset:160 nt
	global_load_dwordx4 v[124:127], v[2:3], off offset:192 nt
	global_load_dwordx4 v[128:131], v[2:3], off offset:224 nt
	global_load_dwordx4 v[132:135], v[2:3], off offset:256 nt
	global_load_dwordx4 v[136:139], v[2:3], off offset:288 nt
	global_load_dwordx4 v[140:143], v[2:3], off offset:320 nt
	global_load_dwordx4 v[144:147], v[2:3], off offset:352 nt
	v_lshl_add_u64 v[0:1], s[2:3], 0, v[152:153]
	s_mul_i32 s10, s6, 0x110000
	v_readlane_b32 s2, v252, 15
	v_readlane_b32 s3, v252, 16
	s_add_u32 s6, s2, s10
	s_addc_u32 s7, s3, 0
	s_lshl_b64 s[2:3], s[40:41], 14
	s_add_u32 s6, s6, s2
	s_addc_u32 s7, s7, s3
	v_lshl_add_u64 v[2:3], s[6:7], 0, v[152:153]
	s_add_i32 s6, s94, 0
	v_lshl_add_u64 v[0:1], v[0:1], 0, s[94:95]
	s_mov_b32 m0, s6
	s_nop 0
	s_barrier
	global_load_lds_dwordx4 v[0:1], off
	v_lshl_add_u64 v[4:5], v[0:1], 0, s[72:73]
	s_add_i32 m0, s64, 0
	v_lshl_add_u64 v[0:1], v[0:1], 0, s[26:27]
	global_load_lds_dwordx4 v[4:5], off
	s_add_i32 m0, s65, 0
	v_lshl_add_u64 v[2:3], v[2:3], 0, s[94:95]
	global_load_lds_dwordx4 v[0:1], off
	s_add_i32 m0, s6, 0x3000
	v_lshl_add_u64 v[0:1], v[2:3], 0, s[72:73]
	global_load_lds_dwordx4 v[2:3], off
	s_add_i32 m0, s6, 0x8000
	s_add_u32 s2, s10, s2
	global_load_lds_dwordx4 v[0:1], off
	s_addc_u32 s3, 0, s3
	v_lshl_add_u64 v[160:161], v[156:157], 0, s[2:3]
	s_add_u32 s2, s8, s5
	v_mov_b32_e32 v96, v97
	s_addc_u32 s3, 0, s9
	v_mov_b32_e32 v98, v97
	v_mov_b32_e32 v99, v97
	v_mov_b32_e32 v100, v97
	v_mov_b32_e32 v101, v97
	v_mov_b32_e32 v102, v97
	v_mov_b32_e32 v103, v97
	v_mov_b32_e32 v104, v97
	v_mov_b32_e32 v105, v97
	v_mov_b32_e32 v106, v97
	v_mov_b32_e32 v107, v97
	v_mov_b32_e32 v108, v97
	v_mov_b32_e32 v109, v97
	v_mov_b32_e32 v110, v97
	v_mov_b32_e32 v111, v97
	v_mov_b64_e32 v[48:49], v[96:97]
	v_mov_b64_e32 v[32:33], v[96:97]
	v_mov_b64_e32 v[16:17], v[96:97]
	v_mov_b64_e32 v[0:1], v[96:97]
	v_lshl_add_u64 v[162:163], v[156:157], 0, s[2:3]
	s_mov_b32 s2, 0
	v_mov_b32_e32 v80, 0xf149f2ca
	v_mov_b32_e32 v81, 0
	v_mov_b64_e32 v[50:51], v[98:99]
	v_mov_b64_e32 v[52:53], v[100:101]
	v_mov_b64_e32 v[54:55], v[102:103]
	v_mov_b64_e32 v[56:57], v[104:105]
	v_mov_b64_e32 v[58:59], v[106:107]
	v_mov_b64_e32 v[60:61], v[108:109]
	v_mov_b64_e32 v[62:63], v[110:111]
	v_mov_b64_e32 v[34:35], v[98:99]
	v_mov_b64_e32 v[36:37], v[100:101]
	v_mov_b64_e32 v[38:39], v[102:103]
	v_mov_b64_e32 v[40:41], v[104:105]
	v_mov_b64_e32 v[42:43], v[106:107]
	v_mov_b64_e32 v[44:45], v[108:109]
	v_mov_b64_e32 v[46:47], v[110:111]
	v_mov_b64_e32 v[18:19], v[98:99]
	v_mov_b64_e32 v[20:21], v[100:101]
	v_mov_b64_e32 v[22:23], v[102:103]
	v_mov_b64_e32 v[24:25], v[104:105]
	v_mov_b64_e32 v[26:27], v[106:107]
	v_mov_b64_e32 v[28:29], v[108:109]
	v_mov_b64_e32 v[30:31], v[110:111]
	v_mov_b64_e32 v[2:3], v[98:99]
	v_mov_b64_e32 v[4:5], v[100:101]
	v_mov_b64_e32 v[6:7], v[102:103]
	v_mov_b64_e32 v[8:9], v[104:105]
	v_mov_b64_e32 v[10:11], v[106:107]
	v_mov_b64_e32 v[12:13], v[108:109]
	v_mov_b64_e32 v[14:15], v[110:111]

.LBB0_817:
	v_lshl_add_u64 v[0:1], v[184:185], 1, v[0:1]
	global_load_dwordx4 v[114:117], v[0:1], off nt
	global_load_dwordx4 v[118:121], v[0:1], off offset:32 nt
	global_load_dwordx4 v[122:125], v[0:1], off offset:64 nt
	global_load_dwordx4 v[126:129], v[0:1], off offset:96 nt
	s_xor_b64 s[8:9], s[0:1], -1
	s_and_b64 vcc, exec, s[8:9]
	s_nop 0
	s_barrier
	s_cbranch_vccnz .LBB0_821
	v_mov_b32_e32 v0, 0xff800000
	s_and_saveexec_b64 s[0:1], s[42:43]
	s_cbranch_execz .LBB0_820
	v_lshl_add_u64 v[0:1], v[148:149], 2, v[6:7]
	global_load_dword v0, v[0:1], off
	s_waitcnt vmcnt(0)
	v_mul_f32_e32 v0, 0x3fb8aa3b, v0
